# v8 + P4c: group-norm weight/bias of all heads staged once in LDS, 8 global loads per wave and item become ds_read_b128 (item loop is vector-memory-instruction bound), waits recomputed
# speedup vs baseline: 1.0143x; 1.0115x over previous
; __device__ __forceinline__ void chunk_out(const PBArgs& A, unsigned char* lds, int G_, int wave, int lane) {
;     const bf16* Y0g = (const bf16*)(A.dout + DO_Y0); const bf16* RPg = (const bf16*)(A.dout + DO_RP); const bf16* MC = (const bf16*)(A.ws + WS_MC);
;     const bf16* Vr = (const bf16*)(A.ws + WS_V); const bf16* Gt = (const bf16*)(A.ws + WS_HBUF); const float* RK = (const float*)(A.ws + WS_RK);
;     bf16* YA = (bf16*)(A.ws + WS_YA);
;     const int fr = lane & 15, fq = lane >> 4, tt = wave & 3, half = wave >> 2;
;     unsigned char* ostg = lds + wave * 2304;
;     bf16x8 nbR[2], naM[4][2]; u32x2 ny0[4]; u32x4 nrv[2], nrg[2]; f32x4 nr4;
;     ...
;     const int it0 = blockIdx.x * 2 + half;
;     if (it0 < 4096) CO_LOAD(it0);
;     ...
;             const f32x4 lg = *(const f32x4*)(A.lnx_g + h * 64 + vi * 16 + fq * 4), lb = *(const f32x4*)(A.lnx_b + h * 64 + vi * 16 + fq * 4);
.LBB0_575:
	s_or_b64 exec, exec, s[0:1]
	s_lshl_b32 s0, s68, 1
	v_readlane_b32 s1, v241, 27
	s_add_i32 s0, s1, s0
	s_cmpk_lt_i32 s0, 0x1000
	s_movk_i32 s2, 0x1000
	s_waitcnt lgkmcnt(0)
	s_barrier
	s_waitcnt vmcnt(3)
	v_mbcnt_lo_u32_b32 v60, -1, 0
	v_mbcnt_hi_u32_b32 v60, -1, v60
	s_cbranch_scc0 .LBB0_578
	s_add_u32 s3, s28, 0x19800000
	s_addc_u32 s16, s29, 0
	s_add_u32 s14, s26, 0x4000000
	s_addc_u32 s15, s27, 0
	v_readlane_b32 s1, v242, 17
	s_add_u32 s8, s26, 0x6000000
	s_mulk_i32 s1, 0x900
	s_addc_u32 s9, s27, 0
	s_add_i32 s17, s1, 0
	v_readlane_b32 s1, v242, 0
	s_bfe_u32 s18, s1, 0x20006
	s_ashr_i32 s1, s0, 31
	v_lshlrev_b32_e32 v94, 3, v60
	s_lshl_b64 s[6:7], s[0:1], 13
	v_lshl_add_u32 v0, s18, 10, v94
	s_add_u32 s10, s8, s6
	v_ashrrev_i32_e32 v1, 31, v0
	s_addc_u32 s11, s9, s7
	v_lshlrev_b64 v[62:63], 1, v[0:1]
	v_lshl_add_u64 v[4:5], s[10:11], 0, v[62:63]
	s_add_u32 s10, s3, s6
	s_addc_u32 s11, s16, s7
	v_lshlrev_b32_e32 v8, 2, v60
	s_add_u32 s6, s14, s6
	v_ashrrev_i32_e32 v9, 31, v8
	s_addc_u32 s7, s15, s7
	v_lshlrev_b64 v[64:65], 1, v[8:9]
	s_mov_b32 s5, 0
	v_lshl_add_u64 v[8:9], s[6:7], 0, v[64:65]
	s_lshl_b32 s4, s18, 9
	v_ashrrev_i32_e32 v95, 31, v94
	v_lshl_add_u64 v[20:21], v[8:9], 0, s[4:5]
	v_add_u32_e32 v96, 0x800, v94
	v_add_u32_e32 v98, 0xa00, v94
	v_add_u32_e32 v100, 0xc00, v94
	v_add_u32_e32 v102, 0xe00, v94
	v_lshl_add_u64 v[10:11], v[94:95], 1, s[10:11]
	v_ashrrev_i32_e32 v97, 31, v96
	v_ashrrev_i32_e32 v99, 31, v98
	v_add_co_u32_e32 v40, vcc, s2, v20
	v_ashrrev_i32_e32 v101, 31, v100
	v_ashrrev_i32_e32 v103, 31, v102
	global_load_dwordx4 v[0:3], v[4:5], off
	s_nop 0
	global_load_dwordx4 v[4:7], v[4:5], off offset:1024
	s_nop 0
	global_load_dwordx4 v[32:35], v[10:11], off
	global_load_dwordx4 v[36:39], v[10:11], off offset:1024
	global_load_dwordx4 v[16:19], v[10:11], off offset:2048
	global_load_dwordx4 v[24:27], v[10:11], off offset:3072
	global_load_dwordx2 v[112:113], v[20:21], off
	global_load_dwordx2 v[108:109], v[20:21], off offset:2048
	v_lshl_add_u64 v[8:9], v[96:97], 1, s[10:11]
	v_lshl_add_u64 v[12:13], v[98:99], 1, s[10:11]
	v_addc_co_u32_e32 v41, vcc, 0, v21, vcc
	v_lshl_add_u64 v[20:21], v[100:101], 1, s[10:11]
	v_lshl_add_u64 v[28:29], v[102:103], 1, s[10:11]
	s_ashr_i32 s10, s0, 6
	s_ashr_i32 s11, s10, 31
	s_lshl_b32 s1, s0, 6
	s_lshl_b64 s[12:13], s[10:11], 12
	s_and_b32 s1, s1, 0xfc0
	s_or_b32 s7, s12, s1
	s_lshl_b32 s6, s18, 4
	s_or_b32 s12, s7, s6
	s_lshl_b64 s[12:13], s[12:13], 7
	global_load_dwordx4 v[8:11], v[8:9], off
	s_nop 0
	global_load_dwordx4 v[12:15], v[12:13], off
	s_nop 0
	global_load_dwordx4 v[20:23], v[20:21], off
	s_nop 0
	global_load_dwordx4 v[28:31], v[28:29], off
	s_nop 0
	global_load_dwordx2 v[114:115], v[40:41], off
	global_load_dwordx2 v[110:111], v[40:41], off offset:2048
	s_add_u32 s18, s70, s12
	v_lshlrev_b32_e32 v40, 4, v60
	s_addc_u32 s19, s71, s13
	v_and_b32_e32 v66, 0x70, v40
	v_mov_b32_e32 v67, 0
	v_lshl_add_u64 v[48:49], s[18:19], 0, v[66:67]
	v_readlane_b32 s18, v241, 19
	v_readlane_b32 s19, v241, 20
	s_add_u32 s12, s18, s12
	s_addc_u32 s13, s19, s13
	v_lshl_add_u64 v[50:51], s[12:13], 0, v[66:67]
	s_ashr_i32 s12, s0, 9
	s_ashr_i32 s13, s12, 31
	v_and_b32_e32 v92, 15, v60
	s_lshl_b64 s[12:13], s[12:13], 12
	s_waitcnt vmcnt(16)
	v_or_b32_e32 v56, s12, v92
	v_ashrrev_i32_e32 v104, 3, v60
	v_or_b32_e32 v56, s1, v56
	v_add_u32_e32 v106, 8, v104
	v_or_b32_e32 v56, s6, v56
	v_mov_b32_e32 v57, s13
	v_readlane_b32 s22, v241, 48
	v_ashrrev_i32_e32 v105, 31, v104
	v_ashrrev_i32_e32 v107, 31, v106
	v_lshlrev_b64 v[56:57], 7, v[56:57]
	v_readlane_b32 s23, v241, 49
	s_lshl_b32 s1, s10, 4
	v_lshlrev_b64 v[40:41], 7, v[104:105]
	v_lshlrev_b64 v[52:53], 7, v[106:107]
	v_lshl_add_u64 v[56:57], s[22:23], 0, v[56:57]
	s_and_b32 s10, s1, 0x70
	s_mov_b32 s11, s5
	v_lshl_add_u64 v[42:43], v[48:49], 0, v[40:41]
	v_lshl_add_u64 v[40:41], v[50:51], 0, v[40:41]
	v_lshl_add_u64 v[48:49], v[48:49], 0, v[52:53]
	v_lshl_add_u64 v[50:51], v[50:51], 0, v[52:53]
	v_lshl_add_u64 v[56:57], v[56:57], 0, s[10:11]
	global_load_dwordx4 v[44:47], v[42:43], off
	s_nop 0
	global_load_dwordx4 v[40:43], v[40:41], off
	s_nop 0
	global_load_dwordx4 v[52:55], v[48:49], off
	s_nop 0
	global_load_dwordx4 v[48:51], v[50:51], off
	v_ashrrev_i32_e32 v70, 4, v60
	global_load_dwordx4 v[56:59], v[56:57], off
	s_movk_i32 s1, 0x90
	v_mov_b32_e32 v71, s17
	v_lshlrev_b32_e32 v74, 3, v70
	v_lshlrev_b32_e32 v70, 2, v70
	v_readlane_b32 s36, v242, 1
	v_mad_u32_u24 v73, v92, s1, v71
	v_lshl_add_u64 v[64:65], s[14:15], 0, v[64:65]
	v_ashrrev_i32_e32 v71, 31, v70
	v_readlane_b32 s38, v242, 3
	v_readlane_b32 s39, v242, 4
	v_readlane_b32 s40, v242, 5
	v_readlane_b32 s41, v242, 6
	v_lshlrev_b64 v[60:61], 6, v[104:105]
	v_lshlrev_b64 v[68:69], 6, v[106:107]
	v_add_u32_e32 v72, s17, v66
	v_lshl_add_u64 v[116:117], s[70:71], 0, v[66:67]
	v_lshl_add_u64 v[118:119], s[18:19], 0, v[66:67]
	v_lshl_add_u64 v[120:121], s[74:75], 0, v[66:67]
	v_mul_lo_u32 v66, v104, s1
	v_lshl_add_u64 v[122:123], v[64:65], 0, s[4:5]
	v_lshl_add_u64 v[124:125], s[8:9], 0, v[62:63]
	v_lshlrev_b64 v[62:63], 2, v[70:71]
	s_mov_b64 s[18:19], s[38:39]
	s_mov_b64 s[20:21], s[40:41]
	s_lshl_b32 s1, s68, 7
	v_readlane_b32 s4, v241, 23
	s_mov_b32 s7, s5
	s_lshl_b32 s10, s30, 1
	v_lshl_add_u64 v[126:127], s[18:19], 0, v[62:63]
	v_lshl_add_u64 v[128:129], s[20:21], 0, v[62:63]
	s_add_i32 s11, s1, s4
	s_lshl_b32 s12, s30, 7
	v_add_u32_e32 v93, v72, v66
	v_add_u32_e32 v144, v73, v74
	v_lshlrev_b64 v[130:131], 1, v[60:61]
	v_lshlrev_b64 v[132:133], 1, v[68:69]
	v_mov_b32_e32 v145, 0x3a27c5ac
	v_readlane_b32 s37, v242, 2
	v_readlane_b32 s42, v242, 7
	v_readlane_b32 s43, v242, 8
	v_readlane_b32 s44, v242, 9
	v_readlane_b32 s45, v242, 10
	v_readlane_b32 s46, v242, 11
	v_readlane_b32 s47, v242, 12
	v_readlane_b32 s48, v242, 13
	v_readlane_b32 s49, v242, 14
	v_readlane_b32 s50, v242, 15
	v_readlane_b32 s51, v242, 16
	v_mbcnt_lo_u32_b32 v154, -1, 0
	v_mbcnt_hi_u32_b32 v154, -1, v154
	v_readlane_b32 s98, v242, 17
	s_lshl_b32 s99, s98, 8
	v_lshl_add_u32 v155, v154, 2, s99
	v_readlane_b32 s100, v242, 3
	v_readlane_b32 s101, v242, 4
	s_nop 4
	global_load_dword v156, v155, s[100:101]
	v_readlane_b32 s100, v242, 5
	v_readlane_b32 s101, v242, 6
	s_nop 4
	global_load_dword v157, v155, s[100:101]
	v_add_u32_e32 v158, 32768, v155
	s_waitcnt vmcnt(0)
	ds_write_b32 v158, v156
	ds_write_b32 v158, v157 offset:2048
	v_lshrrev_b32_e32 v159, 4, v154
	v_lshlrev_b32_e32 v159, 4, v159
	v_add_u32_e32 v159, 32768, v159
	s_waitcnt lgkmcnt(0)
	s_barrier
; #define LDS_WAIT() asm volatile("s_waitcnt lgkmcnt(0)" ::: "memory")
; __device__ __forceinline__ void chunk_out(const PBArgs& A, unsigned char* lds, int G_, int wave, int lane) {
;     ...
;     for (int it = it0; it < 4096; it += 2 * G_) {
;         const int bh = it >> 6, ck = it & 63, b = bh >> 3, h = bh & 7;
;         bf16x8 bR[2], aM[4][2]; u32x2 y0[4], vv[4], gg[4]; u32x4 rv[2], rg[2];
; #pragma unroll
;         for (int ks = 0; ks < 2; ++ks) bR[ks] = nbR[ks];
; #pragma unroll
;         for (int vi = 0; vi < 4; ++vi) { aM[vi][0] = naM[vi][0]; aM[vi][1] = naM[vi][1]; y0[vi] = ny0[vi]; }
; #pragma unroll
;         for (int j = 0; j < 2; ++j) { rv[j] = nrv[j]; rg[j] = nrg[j]; }
;         const float rk = (nr4[0] + nr4[1]) + (nr4[2] + nr4[3]);
;         {
; #pragma unroll
;             for (int j = 0; j < 2; ++j) { const int tk = (lane >> 3) + 8 * j, c16 = lane & 7; *(u32x4*)(ostg + tk * 144 + c16 * 16) = rv[j]; }
;             LDS_WAIT();
; #pragma unroll
;             for (int vi = 0; vi < 4; ++vi) vv[vi] = *(const u32x2*)(ostg + fr * 144 + (vi * 16 + fq * 4) * 2);
;             LDS_WAIT();
; #pragma unroll
;             for (int j = 0; j < 2; ++j) { const int tk = (lane >> 3) + 8 * j, c16 = lane & 7; *(u32x4*)(ostg + tk * 144 + c16 * 16) = rg[j]; }
;             LDS_WAIT();
; #pragma unroll
;             for (int vi = 0; vi < 4; ++vi) gg[vi] = *(const u32x2*)(ostg + fr * 144 + (vi * 16 + fq * 4) * 2);
;             LDS_WAIT();
;         }
;         f32x4 c[4];
; #pragma unroll
;         for (int vi = 0; vi < 4; ++vi) {
;             c[vi] = bf4(y0[vi]);
; #pragma unroll
;             for (int ks = 0; ks < 2; ++ks) c[vi] = __builtin_amdgcn_mfma_f32_16x16x32_bf16(aM[vi][ks], bR[ks], c[vi], 0, 0, 0);
;         }
;         { const int itn = (it + 2 * G_ < 4096) ? it + 2 * G_ : it; CO_LOAD(itn); }
;         float sm = 0.f;
; #pragma unroll
;         for (int vi = 0; vi < 4; ++vi) sm += (c[vi][0] + c[vi][1]) + (c[vi][2] + c[vi][3]);
;         sm = rows4_sum(sm);
;         const float mu = sm * (1.0f / 64.0f);
;         float q = 0.f;
; #pragma unroll
;         for (int vi = 0; vi < 4; ++vi) { c[vi] = c[vi] - mu; q += (c[vi][0] * c[vi][0] + c[vi][1] * c[vi][1]) + (c[vi][2] * c[vi][2] + c[vi][3] * c[vi][3]); }
;         q = rows4_sum(q);
;         const float rs = rsqrtf(q * (1.0f / 64.0f) + 64e-5f);
.LBB0_577:
	s_waitcnt vmcnt(4)
	ds_write_b128 v93, v[44:47]
	s_waitcnt vmcnt(2)
	ds_write_b128 v93, v[52:55] offset:1152
	s_waitcnt lgkmcnt(0)
	ds_read2_b64 v[68:71], v144 offset1:4
	ds_read2_b64 v[60:63], v144 offset0:8 offset1:12
	s_waitcnt lgkmcnt(0)
	ds_write_b128 v93, v[40:43]
	s_waitcnt vmcnt(1)
	ds_write_b128 v93, v[48:51] offset:1152
	v_lshlrev_b32_e32 v40, 16, v112
	v_and_b32_e32 v41, 0xffff0000, v112
	v_lshlrev_b32_e32 v42, 16, v113
	v_and_b32_e32 v43, 0xffff0000, v113
	s_ashr_i32 s8, s0, 9
	s_and_b32 s14, s0, 0x1c0
	v_mfma_f32_16x16x32_bf16 v[32:35], v[32:35], v[0:3], v[40:43]
	s_add_i32 s13, s0, s10
	s_cmpk_lt_i32 s13, 0x1000
	s_cselect_b64 s[18:19], -1, 0
	v_mfma_f32_16x16x32_bf16 v[88:91], v[36:39], v[4:7], v[32:35]
	s_and_b64 vcc, s[18:19], exec
	s_cselect_b32 s18, s13, s0
	s_ashr_i32 s19, s18, 31
	s_nop 0
	v_lshlrev_b32_e32 v32, 16, v108
	v_and_b32_e32 v33, 0xffff0000, v108
	v_lshlrev_b32_e32 v34, 16, v109
	v_and_b32_e32 v35, 0xffff0000, v109
	v_add_f32_e32 v136, v88, v89
	v_add_f32_e32 v137, v90, v91
	v_mfma_f32_16x16x32_bf16 v[16:19], v[16:19], v[0:3], v[32:35]
	v_add_f32_e32 v136, v136, v137
	v_add_f32_e32 v136, 0, v136
	s_lshl_b64 s[0:1], s[18:19], 13
	v_mfma_f32_16x16x32_bf16 v[76:79], v[24:27], v[4:7], v[16:19]
	s_add_u32 s20, s3, s0
	s_addc_u32 s21, s16, s1
	s_waitcnt lgkmcnt(0)
	ds_read2_b64 v[72:75], v144 offset1:4
	ds_read2_b64 v[64:67], v144 offset0:8 offset1:12
	v_lshlrev_b32_e32 v16, 16, v114
	v_and_b32_e32 v17, 0xffff0000, v114
	v_lshlrev_b32_e32 v18, 16, v115
	v_and_b32_e32 v19, 0xffff0000, v115
	v_add_f32_e32 v137, v76, v77
	v_add_f32_e32 v138, v78, v79
	v_mfma_f32_16x16x32_bf16 v[8:11], v[8:11], v[0:3], v[16:19]
	v_add_f32_e32 v137, v137, v138
	v_add_f32_e32 v136, v136, v137
	s_waitcnt lgkmcnt(0)
	v_mfma_f32_16x16x32_bf16 v[80:83], v[12:15], v[4:7], v[8:11]
	v_lshl_add_u64 v[12:13], v[98:99], 1, s[20:21]
	s_waitcnt vmcnt(0)
	v_mov_b32_e32 v44, v57
	v_mov_b32_e32 v45, v58
	s_nop 0
	v_lshlrev_b32_e32 v8, 16, v110
	v_and_b32_e32 v9, 0xffff0000, v110
	v_lshlrev_b32_e32 v10, 16, v111
	v_and_b32_e32 v11, 0xffff0000, v111
	v_add_f32_e32 v137, v80, v81
	v_add_f32_e32 v138, v82, v83
	v_mfma_f32_16x16x32_bf16 v[0:3], v[20:23], v[0:3], v[8:11]
	v_add_f32_e32 v137, v137, v138
	v_add_f32_e32 v136, v136, v137
	v_lshl_add_u64 v[20:21], v[122:123], 0, s[0:1]
	v_mfma_f32_16x16x32_bf16 v[84:87], v[28:31], v[4:7], v[0:3]
	v_lshl_add_u64 v[4:5], v[124:125], 0, s[0:1]
	v_add_co_u32_e64 v40, s[0:1], s2, v20
	v_lshl_add_u64 v[8:9], v[94:95], 1, s[20:21]
	s_nop 0
	v_addc_co_u32_e64 v41, s[0:1], 0, v21, s[0:1]
	s_nop 2
	v_add_f32_e32 v137, v84, v85
	v_add_f32_e32 v138, v86, v87
	v_add_f32_e32 v137, v137, v138
	v_add_f32_e32 v136, v136, v137
	v_mov_b32_e32 v137, v136
	s_nop 1
	v_permlane32_swap_b32_e32 v136, v137
	v_add_f32_e32 v136, v136, v137
	v_mov_b32_e32 v137, v136
	s_nop 1
	v_permlane16_swap_b32_e32 v136, v137
	v_add_f32_e32 v136, v136, v137
	v_fmamk_f32 v151, v136, 0xbc800000, v91
	v_fmac_f32_e32 v89, 0xbc800000, v136
	v_fmamk_f32 v150, v136, 0xbc800000, v90
	v_fmamk_f32 v88, v136, 0xbc800000, v88
	v_mul_f32_e32 v90, v89, v89
	v_mul_f32_e32 v91, v151, v151
	v_fmac_f32_e32 v90, v88, v88
	v_fmac_f32_e32 v91, v150, v150
	s_ashr_i32 s0, s18, 6
	v_add_f32_e32 v137, v90, v91
	v_fmamk_f32 v91, v136, 0xbc800000, v79
	v_fmac_f32_e32 v77, 0xbc800000, v136
	s_ashr_i32 s1, s0, 31
	v_fmamk_f32 v90, v136, 0xbc800000, v78
	v_fmamk_f32 v76, v136, 0xbc800000, v76
	v_mul_f32_e32 v78, v77, v77
	v_mul_f32_e32 v79, v91, v91
	global_load_dwordx4 v[0:3], v[4:5], off
	s_nop 0
	global_load_dwordx4 v[4:7], v[4:5], off offset:1024
	s_nop 0
	global_load_dwordx4 v[32:35], v[8:9], off
	global_load_dwordx4 v[36:39], v[8:9], off offset:1024
	global_load_dwordx2 v[112:113], v[20:21], off
	global_load_dwordx4 v[16:19], v[8:9], off offset:2048
	global_load_dwordx4 v[24:27], v[8:9], off offset:3072
	global_load_dwordx2 v[108:109], v[20:21], off offset:2048
	v_lshl_add_u64 v[8:9], v[96:97], 1, s[20:21]
	v_lshl_add_u64 v[20:21], v[100:101], 1, s[20:21]
	v_lshl_add_u64 v[28:29], v[102:103], 1, s[20:21]
	s_lshl_b64 s[20:21], s[0:1], 12
	s_lshl_b32 s1, s18, 6
	s_ashr_i32 s18, s18, 9
	v_fmac_f32_e32 v78, v76, v76
	v_fmac_f32_e32 v79, v90, v90
	s_ashr_i32 s19, s18, 31
	v_add_f32_e32 v78, v78, v79
	v_fmamk_f32 v83, v136, 0xbc800000, v83
	v_fmac_f32_e32 v81, 0xbc800000, v136
	v_mov_b32_e32 v57, v59
	s_lshl_b64 s[18:19], s[18:19], 12
	v_add_f32_e32 v78, v137, v78
	v_fmamk_f32 v82, v136, 0xbc800000, v82
	v_fmamk_f32 v80, v136, 0xbc800000, v80
	v_mul_f32_e32 v79, v81, v81
	v_mul_f32_e32 v137, v83, v83
	v_pk_add_f32 v[134:135], v[44:45], v[56:57]
	s_and_b32 s1, s1, 0xfc0
	v_or_b32_e32 v56, s18, v92
	v_fmac_f32_e32 v79, v80, v80
	v_fmac_f32_e32 v137, v82, v82
	v_or_b32_e32 v56, s1, v56
	v_add_f32_e32 v79, v79, v137
	v_mov_b32_e32 v57, s19
	v_or_b32_e32 v56, s6, v56
	v_add_f32_e32 v137, v79, v78
	v_fmamk_f32 v79, v136, 0xbc800000, v87
	v_fmac_f32_e32 v85, 0xbc800000, v136
	v_lshlrev_b64 v[56:57], 7, v[56:57]
	s_lshl_b32 s0, s0, 4
	v_fmamk_f32 v78, v136, 0xbc800000, v86
	v_fmamk_f32 v84, v136, 0xbc800000, v84
	v_mul_f32_e32 v86, v85, v85
	v_mul_f32_e32 v87, v79, v79
	v_lshl_add_u64 v[56:57], s[22:23], 0, v[56:57]
	s_and_b32 s4, s0, 0x70
	v_fmac_f32_e32 v86, v84, v84
	v_fmac_f32_e32 v87, v78, v78
	v_lshl_add_u64 v[56:57], v[56:57], 0, s[4:5]
	v_add_f32_e32 v86, v86, v87
	s_lshl_b32 s4, s14, 2
	v_add_f32_e32 v86, v86, v137
	v_add_u32_e32 v136, s4, v159
	s_nop 0
	global_load_dwordx4 v[8:11], v[8:9], off
	v_mov_b32_e32 v87, v86
	global_load_dwordx4 v[12:15], v[12:13], off
	s_nop 0
	v_permlane32_swap_b32_e32 v86, v87
	global_load_dwordx2 v[114:115], v[40:41], off
; __device__ __forceinline__ unsigned pk2(float lo, float hi) { f32x2_t v = {lo, hi}; bf16x2_t b = __builtin_convertvector(v, bf16x2_t); return __builtin_bit_cast(unsigned, b); }
; #define LDS_WAIT() asm volatile("s_waitcnt lgkmcnt(0)" ::: "memory")
; __device__ __forceinline__ f32x4 bf4(u32x2 w) { return (f32x4){__uint_as_float(w.x << 16), __uint_as_float(w.x & 0xffff0000u), __uint_as_float(w.y << 16), __uint_as_float(w.y & 0xffff0000u)}; }
; __device__ __forceinline__ void chunk_out(const PBArgs& A, unsigned char* lds, int G_, int wave, int lane) {
;     ...
; #pragma unroll
;         for (int vi = 0; vi < 4; ++vi) {
;             const f32x4 lg = *(const f32x4*)(A.lnx_g + h * 64 + vi * 16 + fq * 4), lb = *(const f32x4*)(A.lnx_b + h * 64 + vi * 16 + fq * 4);
;             const f32x4 o = (c[vi] * rs * lg + lb + bf4(vv[vi]) * rk) * bf4(gg[vi]);
;             *(u32x2*)(ostg + fr * 144 + (vi * 16 + fq * 4) * 2) = (u32x2){pk2(o[0], o[1]), pk2(o[2], o[3])};
;         }
;         LDS_WAIT();
; #pragma unroll
;         for (int j = 0; j < 2; ++j) {
;             const int tk = (lane >> 3) + 8 * j, c16 = lane & 7;
;             const size_t tg = (size_t)b * SEQ + ck * 64 + tt * 16 + tk;
;             *(u32x4*)(YA + tg * 512 + h * 64 + c16 * 8) = *(const u32x4*)(ostg + tk * 144 + c16 * 16);
;         }
;         LDS_WAIT();
	v_add_f32_e32 v86, v86, v87
	global_load_dwordx4 v[20:23], v[20:21], off
	s_nop 0
	global_load_dwordx4 v[28:31], v[28:29], off
	s_nop 0
	global_load_dwordx2 v[110:111], v[40:41], off offset:2048
	ds_read_b128 v[140:143], v136
	ds_read_b128 v[146:149], v136 offset:2048
	v_mov_b32_e32 v87, v86
	s_nop 1
	v_permlane16_swap_b32_e32 v86, v87
	v_add_f32_e32 v86, v86, v87
	v_fmamk_f32 v86, v86, 0x3c800000, v145
	s_mov_b32 s0, 0x800000
	s_or_b32 s20, s20, s1
	v_cmp_gt_f32_e64 s[0:1], s0, v86
	v_mul_f32_e32 v87, 0x4b800000, v86
	s_or_b64 s[20:21], s[20:21], s[6:7]
	v_cndmask_b32_e64 v86, v86, v87, s[0:1]
	v_rsq_f32_e32 v86, v86
	s_lshl_b64 s[20:21], s[20:21], 7
	v_lshl_add_u64 v[48:49], v[116:117], 0, s[20:21]
	v_lshl_add_u64 v[50:51], v[118:119], 0, s[20:21]
	v_mul_f32_e32 v87, 0x45800000, v86
	v_cndmask_b32_e64 v86, v86, v87, s[0:1]
	v_pk_mul_f32 v[152:153], v[88:89], v[86:87] op_sel_hi:[1,0]
	v_pk_mul_f32 v[88:89], v[150:151], v[86:87] op_sel_hi:[1,0]
	v_lshl_add_u64 v[40:41], v[48:49], 0, v[130:131]
	v_lshl_add_u64 v[48:49], v[48:49], 0, v[132:133]
	v_add_f32_e32 v134, v134, v135
	global_load_dwordx4 v[44:47], v[40:41], off
	global_load_dwordx4 v[52:55], v[48:49], off
	v_lshl_add_u64 v[40:41], v[50:51], 0, v[130:131]
	v_lshl_add_u64 v[48:49], v[50:51], 0, v[132:133]
	global_load_dwordx4 v[40:43], v[40:41], off
	s_ashr_i32 s9, s8, 31
	global_load_dwordx4 v[48:51], v[48:49], off
	s_and_b32 s4, s11, 0xfc0
	global_load_dwordx4 v[56:59], v[56:57], off
	s_lshl_b64 s[0:1], s[8:9], 12
	s_or_b32 s4, s4, s6
	s_or_b32 s0, s0, s4
	s_lshl_b32 s4, s14, 1
	s_add_i32 s11, s11, s12
	s_nop 0
	s_waitcnt lgkmcnt(0)
	v_pk_fma_f32 v[88:89], v[142:143], v[88:89], v[148:149]
	v_pk_fma_f32 v[140:141], v[140:141], v[152:153], v[146:147]
	s_nop 0
	v_lshlrev_b32_e32 v142, 16, v68
	v_and_b32_e32 v143, 0xffff0000, v68
	v_lshlrev_b32_e32 v68, 16, v69
	v_and_b32_e32 v69, 0xffff0000, v69
	v_pk_fma_f32 v[140:141], v[134:135], v[142:143], v[140:141] op_sel_hi:[0,1,1]
	v_pk_fma_f32 v[68:69], v[134:135], v[68:69], v[88:89] op_sel_hi:[0,1,1]
	s_nop 0
	v_lshlrev_b32_e32 v88, 16, v72
	v_and_b32_e32 v89, 0xffff0000, v72
	v_lshlrev_b32_e32 v72, 16, v73
	v_and_b32_e32 v73, 0xffff0000, v73
	v_pk_mul_f32 v[68:69], v[68:69], v[72:73]
	v_pk_mul_f32 v[72:73], v[140:141], v[88:89]
	ds_read_b128 v[140:143], v136 offset:64
	ds_read_b128 v[146:149], v136 offset:2112
	v_cvt_pk_bf16_f32 v72, v72, v73
	v_cvt_pk_bf16_f32 v73, v68, v69
	v_pk_mul_f32 v[68:69], v[76:77], v[86:87] op_sel_hi:[1,0]
	v_pk_mul_f32 v[76:77], v[90:91], v[86:87] op_sel_hi:[1,0]
	v_lshlrev_b32_e32 v88, 16, v70
	v_and_b32_e32 v89, 0xffff0000, v70
	v_lshlrev_b32_e32 v70, 16, v71
	v_and_b32_e32 v71, 0xffff0000, v71
	s_nop 0
	s_waitcnt lgkmcnt(0)
	v_pk_fma_f32 v[76:77], v[142:143], v[76:77], v[148:149]
	v_pk_fma_f32 v[68:69], v[140:141], v[68:69], v[146:147]
	v_pk_fma_f32 v[70:71], v[134:135], v[70:71], v[76:77] op_sel_hi:[0,1,1]
	v_pk_fma_f32 v[68:69], v[134:135], v[88:89], v[68:69] op_sel_hi:[0,1,1]
	v_lshlrev_b32_e32 v76, 16, v74
	v_and_b32_e32 v77, 0xffff0000, v74
	v_lshlrev_b32_e32 v74, 16, v75
	v_and_b32_e32 v75, 0xffff0000, v75
	v_pk_mul_f32 v[70:71], v[70:71], v[74:75]
	v_pk_mul_f32 v[68:69], v[68:69], v[76:77]
	v_pk_mul_f32 v[76:77], v[80:81], v[86:87] op_sel_hi:[1,0]
	v_cvt_pk_bf16_f32 v68, v68, v69
	v_cvt_pk_bf16_f32 v69, v70, v71
	ds_write2_b64 v144, v[72:73], v[68:69] offset1:4
	ds_read_b128 v[68:71], v136 offset:128
	ds_read_b128 v[72:75], v136 offset:2176
	v_pk_mul_f32 v[80:81], v[82:83], v[86:87] op_sel_hi:[1,0]
	s_nop 0
	s_waitcnt lgkmcnt(0)
	v_pk_fma_f32 v[68:69], v[68:69], v[76:77], v[72:73]
	v_pk_fma_f32 v[70:71], v[70:71], v[80:81], v[74:75]
	v_lshlrev_b32_e32 v72, 16, v60
	v_and_b32_e32 v73, 0xffff0000, v60
	v_lshlrev_b32_e32 v60, 16, v61
	v_and_b32_e32 v61, 0xffff0000, v61
	v_pk_fma_f32 v[68:69], v[134:135], v[72:73], v[68:69] op_sel_hi:[0,1,1]
	v_pk_fma_f32 v[60:61], v[134:135], v[60:61], v[70:71] op_sel_hi:[0,1,1]
	s_nop 0
	v_lshlrev_b32_e32 v70, 16, v64
	v_and_b32_e32 v71, 0xffff0000, v64
	v_lshlrev_b32_e32 v64, 16, v65
	v_and_b32_e32 v65, 0xffff0000, v65
	v_pk_mul_f32 v[60:61], v[60:61], v[64:65]
	v_pk_mul_f32 v[64:65], v[68:69], v[70:71]
	ds_read_b128 v[68:71], v136 offset:192
	ds_read_b128 v[72:75], v136 offset:2240
	v_cvt_pk_bf16_f32 v64, v64, v65
	v_cvt_pk_bf16_f32 v65, v60, v61
	v_pk_mul_f32 v[60:61], v[84:85], v[86:87] op_sel_hi:[1,0]
	v_pk_mul_f32 v[76:77], v[78:79], v[86:87] op_sel_hi:[1,0]
	s_nop 0
	s_waitcnt lgkmcnt(0)
	v_pk_fma_f32 v[60:61], v[68:69], v[60:61], v[72:73]
	v_pk_fma_f32 v[70:71], v[70:71], v[76:77], v[74:75]
	v_lshlrev_b32_e32 v68, 16, v62
	v_and_b32_e32 v69, 0xffff0000, v62
	v_lshlrev_b32_e32 v62, 16, v63
	v_and_b32_e32 v63, 0xffff0000, v63
	v_pk_fma_f32 v[60:61], v[134:135], v[68:69], v[60:61] op_sel_hi:[0,1,1]
	v_pk_fma_f32 v[62:63], v[134:135], v[62:63], v[70:71] op_sel_hi:[0,1,1]
	v_lshlrev_b32_e32 v68, 16, v66
	v_and_b32_e32 v69, 0xffff0000, v66
	v_lshlrev_b32_e32 v66, 16, v67
	v_and_b32_e32 v67, 0xffff0000, v67
	v_pk_mul_f32 v[62:63], v[62:63], v[66:67]
	v_pk_mul_f32 v[60:61], v[60:61], v[68:69]
	v_lshl_add_u64 v[66:67], s[0:1], 0, v[104:105]
	v_cvt_pk_bf16_f32 v60, v60, v61
	v_cvt_pk_bf16_f32 v61, v62, v63
	ds_write2_b64 v144, v[64:65], v[60:61] offset0:8 offset1:12
	s_waitcnt lgkmcnt(0)
	ds_read_b128 v[60:63], v93
	v_lshl_add_u64 v[64:65], v[120:121], 0, s[4:5]
	v_lshlrev_b64 v[66:67], 10, v[66:67]
	v_lshl_add_u64 v[66:67], v[64:65], 0, v[66:67]
	s_nop 0
	s_waitcnt lgkmcnt(0)
	global_store_dwordx4 v[66:67], v[60:63], off
	ds_read_b128 v[60:63], v93 offset:1152
	v_lshl_add_u64 v[66:67], s[0:1], 0, v[106:107]
	v_lshlrev_b64 v[66:67], 10, v[66:67]
	v_lshl_add_u64 v[64:65], v[64:65], 0, v[66:67]
	s_mov_b32 s0, s13
	s_nop 0
	s_waitcnt lgkmcnt(0)
	global_store_dwordx4 v[64:65], v[60:63], off
	s_waitcnt lgkmcnt(0)
	s_cbranch_vccnz .LBB0_577
